# first grid sync: census counters read with one 16-lane load instead of 16 serial loads
# speedup vs baseline: 1.0039x; 1.0025x over previous
; __global__ void __launch_bounds__(512, 2) mega_fwd(Args a_byval) {
;     ...
;         { const bool ffn_in_seam = (ph >= 2 && ph < 18 && (((ph - 2) & 7) == 0 || ((ph - 2) & 7) == 6)) && (int)gridDim.x == 256;
;           if (it + 1 < it_hi && !ffn_in_seam) grid.sync(); }
.Lgh_spin1:
	s_sleep 1
	global_load_dword v1, v129, s[6:7] sc1
	s_waitcnt vmcnt(0)
	v_cmp_gt_u32_e32 vcc, s0, v1
	s_cbranch_vccnz .Lgh_spin1
	s_mov_b32 s9, 0
	s_mov_b32 s2, 0
	s_mov_b64 s[98:99], exec
	s_mov_b64 exec, 0xffff
	v_mbcnt_lo_u32_b32 v0, -1, 0
	v_lshlrev_b32_e32 v0, 8, v0
	global_load_dword v1, v0, s[12:13] sc1
	s_waitcnt vmcnt(0)
	s_mov_b64 exec, s[98:99]
	v_readlane_b32 s11, v1, 0
	s_nop 0
	s_cmp_lg_u32 s11, 0
	s_cselect_b32 s3, 1, 0
	s_add_i32 s9, s9, s3
	s_cmp_eq_u32 s8, 0x0
	s_cselect_b32 s2, s11, s2
	v_readlane_b32 s11, v1, 1
	s_nop 0
	s_cmp_lg_u32 s11, 0
	s_cselect_b32 s3, 1, 0
	s_add_i32 s9, s9, s3
	s_cmp_eq_u32 s8, 0x100
	s_cselect_b32 s2, s11, s2
	v_readlane_b32 s11, v1, 2
	s_nop 0
	s_cmp_lg_u32 s11, 0
	s_cselect_b32 s3, 1, 0
	s_add_i32 s9, s9, s3
	s_cmp_eq_u32 s8, 0x200
	s_cselect_b32 s2, s11, s2
	v_readlane_b32 s11, v1, 3
	s_nop 0
	s_cmp_lg_u32 s11, 0
	s_cselect_b32 s3, 1, 0
	s_add_i32 s9, s9, s3
	s_cmp_eq_u32 s8, 0x300
	s_cselect_b32 s2, s11, s2
	v_readlane_b32 s11, v1, 4
	s_nop 0
	s_cmp_lg_u32 s11, 0
	s_cselect_b32 s3, 1, 0
	s_add_i32 s9, s9, s3
	s_cmp_eq_u32 s8, 0x400
	s_cselect_b32 s2, s11, s2
	v_readlane_b32 s11, v1, 5
	s_nop 0
	s_cmp_lg_u32 s11, 0
	s_cselect_b32 s3, 1, 0
	s_add_i32 s9, s9, s3
	s_cmp_eq_u32 s8, 0x500
	s_cselect_b32 s2, s11, s2
	v_readlane_b32 s11, v1, 6
	s_nop 0
	s_cmp_lg_u32 s11, 0
	s_cselect_b32 s3, 1, 0
	s_add_i32 s9, s9, s3
	s_cmp_eq_u32 s8, 0x600
	s_cselect_b32 s2, s11, s2
	v_readlane_b32 s11, v1, 7
	s_nop 0
	s_cmp_lg_u32 s11, 0
	s_cselect_b32 s3, 1, 0
	s_add_i32 s9, s9, s3
	s_cmp_eq_u32 s8, 0x700
	s_cselect_b32 s2, s11, s2
	v_readlane_b32 s11, v1, 8
	s_nop 0
	s_cmp_lg_u32 s11, 0
	s_cselect_b32 s3, 1, 0
	s_add_i32 s9, s9, s3
	s_cmp_eq_u32 s8, 0x800
	s_cselect_b32 s2, s11, s2
	v_readlane_b32 s11, v1, 9
	s_nop 0
	s_cmp_lg_u32 s11, 0
	s_cselect_b32 s3, 1, 0
	s_add_i32 s9, s9, s3
	s_cmp_eq_u32 s8, 0x900
	s_cselect_b32 s2, s11, s2
	v_readlane_b32 s11, v1, 10
	s_nop 0
	s_cmp_lg_u32 s11, 0
	s_cselect_b32 s3, 1, 0
	s_add_i32 s9, s9, s3
	s_cmp_eq_u32 s8, 0xa00
	s_cselect_b32 s2, s11, s2
	v_readlane_b32 s11, v1, 11
	s_nop 0
	s_cmp_lg_u32 s11, 0
	s_cselect_b32 s3, 1, 0
	s_add_i32 s9, s9, s3
	s_cmp_eq_u32 s8, 0xb00
	s_cselect_b32 s2, s11, s2
	v_readlane_b32 s11, v1, 12
	s_nop 0
	s_cmp_lg_u32 s11, 0
	s_cselect_b32 s3, 1, 0
	s_add_i32 s9, s9, s3
	s_cmp_eq_u32 s8, 0xc00
	s_cselect_b32 s2, s11, s2
	v_readlane_b32 s11, v1, 13
	s_nop 0
	s_cmp_lg_u32 s11, 0
	s_cselect_b32 s3, 1, 0
	s_add_i32 s9, s9, s3
	s_cmp_eq_u32 s8, 0xd00
	s_cselect_b32 s2, s11, s2
	v_readlane_b32 s11, v1, 14
	s_nop 0
	s_cmp_lg_u32 s11, 0
	s_cselect_b32 s3, 1, 0
	s_add_i32 s9, s9, s3
	s_cmp_eq_u32 s8, 0xe00
	s_cselect_b32 s2, s11, s2
	v_readlane_b32 s11, v1, 15
	s_nop 0
	s_cmp_lg_u32 s11, 0
	s_cselect_b32 s3, 1, 0
	s_add_i32 s9, s9, s3
	s_cmp_eq_u32 s8, 0xf00
	s_cselect_b32 s2, s11, s2
	v_writelane_b32 v255, s2, 57
	v_writelane_b32 v255, s9, 58
	s_branch .Lgh_done
